# P3 rows: same lane-to-column remap as P12 (x f32 row and gains read as contiguous 1 KiB per instruction; bf16 rows as 8-byte pieces)
# baseline (speedup 1.0000x reference)
.LBB0_399:
	s_cmp_lt_i32 s86, 4
	s_cselect_b64 s[2:3], -1, 0
	s_and_b64 s[2:3], s[2:3], s[0:1]
	s_andn2_b64 vcc, exec, s[2:3]
	s_cbranch_vccnz .LBB0_409
	s_add_i32 s0, 0, 0x27e00
	v_mov_b32_e32 v0, v182
	v_mov_b32_e32 v1, s0
	s_add_i32 s0, 0, 0x27e28
	ds_read_b64 v[6:7], v1
	v_mov_b32_e32 v1, s0
	ds_read2_b64 v[2:5], v1 offset1:1
	v_readfirstlane_b32 s0, v0
	s_ashr_i32 s0, s0, 6
	s_lshl_b32 s1, s81, 3
	s_add_i32 s0, s0, s1
	s_waitcnt lgkmcnt(0)
	v_readfirstlane_b32 s4, v6
	v_readfirstlane_b32 s5, v7
	v_readfirstlane_b32 s8, v2
	v_readfirstlane_b32 s9, v3
	v_readfirstlane_b32 s6, v4
	s_cmp_gt_i32 s0, 0xffff
	v_readfirstlane_b32 s7, v5
	s_cbranch_scc1 .LBB0_409
	v_and_b32_e32 v36, 63, v0
	v_lshlrev_b32_e32 v32, 4, v36
	v_mov_b32_e32 v33, 0
	v_lshl_add_u64 v[16:17], s[8:9], 0, v[32:33]
	v_lshl_add_u64 v[34:35], s[6:7], 0, v[32:33]
	flat_load_dwordx4 v[0:3], v[16:17]
	flat_load_dwordx4 v[4:7], v[16:17] offset:1024
	flat_load_dwordx4 v[8:11], v[16:17] offset:2048
	flat_load_dwordx4 v[12:15], v[16:17] offset:3072
	s_nop 0
	flat_load_dwordx4 v[16:19], v[34:35]
	flat_load_dwordx4 v[20:23], v[34:35] offset:1024
	flat_load_dwordx4 v[24:27], v[34:35] offset:2048
	flat_load_dwordx4 v[28:31], v[34:35] offset:3072
	v_lshlrev_b32_e32 v34, 3, v36
	v_mbcnt_lo_u32_b32 v36, -1, 0
	v_mbcnt_hi_u32_b32 v36, -1, v36
	v_and_b32_e32 v37, 64, v36
	v_add_u32_e32 v37, 64, v37
	v_xor_b32_e32 v38, 1, v36
	v_cmp_lt_i32_e32 vcc, v38, v37
	v_mov_b32_e32 v35, v33
	v_lshl_add_u64 v[34:35], s[84:85], 0, v[34:35]
	v_cndmask_b32_e32 v38, v36, v38, vcc
	v_lshlrev_b32_e32 v88, 2, v38
	v_xor_b32_e32 v38, 2, v36
	v_cmp_lt_i32_e32 vcc, v38, v37
	s_mov_b64 s[6:7], 0xc000000
	v_lshl_add_u64 v[52:53], v[34:35], 0, s[6:7]
	v_cndmask_b32_e32 v38, v36, v38, vcc
	v_lshlrev_b32_e32 v89, 2, v38
	v_xor_b32_e32 v38, 4, v36
	v_cmp_lt_i32_e32 vcc, v38, v37
	s_mov_b64 s[6:7], 0x4000000
	v_lshl_add_u64 v[54:55], v[34:35], 0, s[6:7]
	v_cndmask_b32_e32 v38, v36, v38, vcc
	v_lshlrev_b32_e32 v90, 2, v38
	v_xor_b32_e32 v38, 8, v36
	v_cmp_lt_i32_e32 vcc, v38, v37
	v_lshl_add_u64 v[56:57], s[4:5], 0, v[32:33]
	v_mov_b32_e32 v94, 0x358637bd
	v_cndmask_b32_e32 v38, v36, v38, vcc
	v_lshlrev_b32_e32 v91, 2, v38
	v_xor_b32_e32 v38, 16, v36
	v_cmp_lt_i32_e32 vcc, v38, v37
	s_mov_b32 s10, 0xf800000
	v_mov_b32_e32 v95, 0x260
	v_cndmask_b32_e32 v38, v36, v38, vcc
	v_lshlrev_b32_e32 v92, 2, v38
	v_xor_b32_e32 v38, 32, v36
	v_cmp_lt_i32_e32 vcc, v38, v37
	s_nop 1
	v_cndmask_b32_e32 v36, v36, v38, vcc
	v_lshlrev_b32_e32 v93, 2, v36
	s_branch .LBB0_403

.LBB0_403:
	s_ashr_i32 s1, s0, 31
	s_lshl_b64 s[6:7], s[0:1], 11
	v_lshl_add_u64 v[58:59], v[52:53], 0, s[6:7]
	s_waitcnt lgkmcnt(0)
	global_load_dwordx2 v[32:33], v[58:59], off
	global_load_dwordx2 v[34:35], v[58:59], off offset:512
	global_load_dwordx2 v[36:37], v[58:59], off offset:1024
	global_load_dwordx2 v[38:39], v[58:59], off offset:1536
	s_add_i32 s4, s0, s83
	s_min_i32 s8, s4, 0xffff
	s_ashr_i32 s9, s8, 31
	s_lshl_b64 s[12:13], s[8:9], 11
	v_lshl_add_u64 v[40:41], v[52:53], 0, s[12:13]
	global_load_dwordx2 v[68:69], v[40:41], off
	global_load_dwordx2 v[70:71], v[40:41], off offset:512
	global_load_dwordx2 v[48:49], v[40:41], off offset:1024
	global_load_dwordx2 v[50:51], v[40:41], off offset:1536
	s_lshl_b64 s[0:1], s[0:1], 12
	v_lshl_add_u64 v[42:43], v[56:57], 0, s[0:1]
	flat_load_dwordx4 v[72:75], v[42:43]
	flat_load_dwordx4 v[76:79], v[42:43] offset:1024
	flat_load_dwordx4 v[82:85], v[42:43] offset:2048
	flat_load_dwordx4 v[96:99], v[42:43] offset:3072
	s_lshl_b64 s[0:1], s[8:9], 12
	v_lshl_add_u64 v[60:61], v[56:57], 0, s[0:1]
	flat_load_dwordx4 v[44:47], v[60:61]
	flat_load_dwordx4 v[40:43], v[60:61] offset:1024
	s_cmp_lt_i32 s4, 0x10000
	s_waitcnt vmcnt(0)
	v_and_b32_e32 v81, 0xffff0000, v32
	v_and_b32_e32 v87, 0xffff0000, v33
	v_and_b32_e32 v101, 0xffff0000, v34
	v_and_b32_e32 v103, 0xffff0000, v35
	v_lshlrev_b32_e32 v80, 16, v32
	v_lshlrev_b32_e32 v86, 16, v33
	v_lshlrev_b32_e32 v100, 16, v34
	v_lshlrev_b32_e32 v102, 16, v35
	v_and_b32_e32 v105, 0xffff0000, v36
	v_and_b32_e32 v107, 0xffff0000, v37
	v_mul_f32_e32 v32, v81, v81
	v_mul_f32_e32 v33, v87, v87
	v_mul_f32_e32 v34, v101, v101
	v_mul_f32_e32 v35, v103, v103
	v_lshlrev_b32_e32 v104, 16, v36
	v_lshlrev_b32_e32 v106, 16, v37
	v_and_b32_e32 v109, 0xffff0000, v38
	v_and_b32_e32 v111, 0xffff0000, v39
	v_mul_f32_e32 v36, v105, v105
	v_mul_f32_e32 v37, v107, v107
	v_fmac_f32_e32 v32, v80, v80
	v_fmac_f32_e32 v33, v86, v86
	v_fmac_f32_e32 v34, v100, v100
	v_fmac_f32_e32 v35, v102, v102
	v_lshlrev_b32_e32 v108, 16, v38
	v_lshlrev_b32_e32 v110, 16, v39
	v_mul_f32_e32 v38, v109, v109
	v_mul_f32_e32 v39, v111, v111
	v_fmac_f32_e32 v36, v104, v104
	v_fmac_f32_e32 v37, v106, v106
	v_add_f32_e32 v32, v32, v33
	v_add_f32_e32 v33, v34, v35
	v_fmac_f32_e32 v38, v108, v108
	v_fmac_f32_e32 v39, v110, v110
	v_add_f32_e32 v34, v36, v37
	v_add_f32_e32 v32, v32, v33
	v_add_f32_e32 v35, v38, v39
	v_add_f32_e32 v32, v32, v34
	v_add_f32_e32 v32, v35, v32
	s_nop 1
	v_lshlrev_b32_e32 v66, 16, v71
	v_and_b32_e32 v67, 0xffff0000, v71
	v_lshlrev_b32_e32 v64, 16, v68
	v_and_b32_e32 v65, 0xffff0000, v68
	s_waitcnt lgkmcnt(0)
	v_add_f32_dpp v32, v32, v32 quad_perm:[1,0,3,2] row_mask:0xf bank_mask:0xf
	s_nop 1
	v_lshlrev_b32_e32 v68, 16, v69
	v_and_b32_e32 v69, 0xffff0000, v69
	s_waitcnt lgkmcnt(0)
	v_add_f32_dpp v32, v32, v32 quad_perm:[2,3,0,1] row_mask:0xf bank_mask:0xf
	s_nop 1
	s_waitcnt lgkmcnt(0)
	v_add_f32_dpp v32, v32, v32 row_half_mirror row_mask:0xf bank_mask:0xf
	s_nop 1
	s_waitcnt lgkmcnt(0)
	v_add_f32_dpp v62, v32, v32 row_mirror row_mask:0xf bank_mask:0xf
	v_mov_b32_e32 v63, v62
	flat_load_dwordx4 v[36:39], v[60:61] offset:2048
	flat_load_dwordx4 v[32:35], v[60:61] offset:3072
	s_waitcnt lgkmcnt(0)
	v_permlane16_swap_b32_e32 v62, v63
	v_add_f32_e32 v60, v62, v63
	v_mov_b32_e32 v61, v60
	v_lshlrev_b32_e32 v62, 16, v70
	v_and_b32_e32 v63, 0xffff0000, v70
	s_waitcnt lgkmcnt(0)
	v_permlane32_swap_b32_e32 v60, v61
	v_add_f32_e32 v60, v60, v61
	v_fmamk_f32 v60, v60, 0x3a800000, v94
	v_mul_f32_e32 v61, 0x4f800000, v60
	v_cmp_gt_f32_e32 vcc, s10, v60
	s_nop 1
	v_cndmask_b32_e32 v61, v60, v61, vcc
	v_sqrt_f32_e32 v70, v61
	v_lshlrev_b32_e32 v60, 16, v48
	v_add_u32_e32 v71, -1, v70
	v_add_u32_e32 v112, 1, v70
	v_fma_f32 v113, -v71, v70, v61
	v_fma_f32 v114, -v112, v70, v61
	v_cmp_ge_f32_e64 s[0:1], 0, v113
	s_nop 1
	v_cndmask_b32_e64 v70, v70, v71, s[0:1]
	v_cmp_lt_f32_e64 s[0:1], 0, v114
	s_nop 1
	v_cndmask_b32_e64 v70, v70, v112, s[0:1]
	v_mul_f32_e32 v71, 0x37800000, v70
	v_cndmask_b32_e32 v70, v70, v71, vcc
	v_cmp_class_f32_e32 vcc, v61, v95
	s_nop 1
	v_cndmask_b32_e32 v70, v70, v61, vcc
	v_div_scale_f32 v71, s[0:1], v70, v70, 1.0
	v_rcp_f32_e32 v112, v71
	v_and_b32_e32 v61, 0xffff0000, v48
	v_div_scale_f32 v48, vcc, 1.0, v70, 1.0
	v_fma_f32 v113, -v71, v112, 1.0
	v_fmac_f32_e32 v112, v113, v112
	v_mul_f32_e32 v113, v48, v112
	v_fma_f32 v114, -v71, v113, v48
	v_fmac_f32_e32 v113, v114, v112
	v_fma_f32 v48, -v71, v113, v48
	v_div_fmas_f32 v48, v48, v112, v113
	v_div_fixup_f32 v48, v48, v70, 1.0
	v_mul_f32_e32 v48, 0.5, v48
	v_pk_mul_f32 v[80:81], v[48:49], v[80:81] op_sel_hi:[0,1]
	v_pk_mul_f32 v[70:71], v[48:49], v[86:87] op_sel_hi:[0,1]
	v_pk_mul_f32 v[86:87], v[48:49], v[100:101] op_sel_hi:[0,1]
	v_pk_mul_f32 v[100:101], v[48:49], v[102:103] op_sel_hi:[0,1]
	v_pk_mul_f32 v[102:103], v[48:49], v[104:105] op_sel_hi:[0,1]
	v_pk_mul_f32 v[104:105], v[48:49], v[106:107] op_sel_hi:[0,1]
	v_pk_mul_f32 v[106:107], v[48:49], v[108:109] op_sel_hi:[0,1]
	v_pk_mul_f32 v[108:109], v[48:49], v[110:111] op_sel_hi:[0,1]
	v_pk_fma_f32 v[70:71], v[2:3], v[70:71], v[74:75]
	v_pk_fma_f32 v[72:73], v[0:1], v[80:81], v[72:73]
	v_pk_fma_f32 v[74:75], v[6:7], v[100:101], v[78:79]
	v_pk_fma_f32 v[78:79], v[4:5], v[86:87], v[76:77]
	v_pk_fma_f32 v[80:81], v[10:11], v[104:105], v[84:85]
	v_pk_fma_f32 v[84:85], v[14:15], v[108:109], v[98:99]
	v_pk_fma_f32 v[86:87], v[12:13], v[106:107], v[96:97]
	v_pk_mul_f32 v[76:77], v[70:71], v[70:71]
	v_pk_mul_f32 v[96:97], v[72:73], v[72:73]
	v_pk_mul_f32 v[98:99], v[74:75], v[74:75]
	v_pk_mul_f32 v[100:101], v[78:79], v[78:79]
	v_pk_fma_f32 v[82:83], v[8:9], v[102:103], v[82:83]
	v_pk_mov_b32 v[104:105], v[96:97], v[76:77] op_sel:[1,0]
	v_mov_b32_e32 v97, v77
	v_pk_mov_b32 v[76:77], v[100:101], v[98:99] op_sel:[1,0]
	v_mov_b32_e32 v101, v99
	v_mul_f32_e32 v48, v82, v82
	v_mul_f32_e32 v102, v80, v80
	v_pk_add_f32 v[96:97], v[104:105], v[96:97]
	v_pk_add_f32 v[76:77], v[76:77], v[100:101]
	v_pk_fma_f32 v[98:99], v[82:83], v[82:83], v[48:49] op_sel_hi:[1,1,0]
	v_pk_fma_f32 v[102:103], v[80:81], v[80:81], v[102:103] op_sel_hi:[1,1,0]
	v_pk_add_f32 v[96:97], v[96:97], v[96:97] op_sel_hi:[0,1]
	v_pk_add_f32 v[76:77], v[76:77], v[76:77] op_sel_hi:[0,1]
	v_mul_f32_e32 v98, v86, v86
	v_mul_f32_e32 v102, v87, v87
	v_mul_f32_e32 v96, v84, v84
	v_mul_f32_e32 v76, v85, v85
	v_pk_add_f32 v[98:99], v[98:99], v[102:103]
	v_pk_add_f32 v[76:77], v[96:97], v[76:77]
	v_mul_f32_e32 v100, v63, v63
	v_pk_add_f32 v[76:77], v[98:99], v[76:77]
	v_mul_f32_e32 v98, v65, v65
	v_add_f32_e32 v96, v76, v77
	s_nop 1
	v_mul_f32_e32 v99, v69, v69
	v_fmac_f32_e32 v98, v64, v64
	v_fmac_f32_e32 v99, v68, v68
	v_add_f32_e32 v98, v98, v99
	s_waitcnt lgkmcnt(0)
	v_add_f32_dpp v96, v96, v96 quad_perm:[1,0,3,2] row_mask:0xf bank_mask:0xf
	s_nop 1
	v_mul_f32_e32 v101, v67, v67
	v_fmac_f32_e32 v100, v62, v62
	v_fmac_f32_e32 v101, v66, v66
	v_and_b32_e32 v77, 0xffff0000, v49
	s_waitcnt lgkmcnt(0)
	v_add_f32_dpp v96, v96, v96 quad_perm:[2,3,0,1] row_mask:0xf bank_mask:0xf
	s_nop 1
	v_lshlrev_b32_e32 v76, 16, v49
	v_lshlrev_b32_e32 v48, 16, v50
	v_and_b32_e32 v49, 0xffff0000, v50
	v_lshlrev_b32_e32 v50, 16, v51
	s_waitcnt lgkmcnt(0)
	v_add_f32_dpp v96, v96, v96 row_half_mirror row_mask:0xf bank_mask:0xf
	s_nop 1
	v_and_b32_e32 v51, 0xffff0000, v51
	v_mul_f32_e32 v102, v61, v61
	v_fmac_f32_e32 v102, v60, v60
	s_waitcnt lgkmcnt(0)
	v_add_f32_dpp v99, v96, v96 row_mirror row_mask:0xf bank_mask:0xf
	v_mov_b32_e32 v103, v99
	v_add_f32_e32 v96, v100, v101
	v_add_f32_e32 v100, v98, v96
	v_cvt_pk_bf16_f32 v96, v72, v73
	v_cvt_pk_bf16_f32 v97, v70, v71
	s_waitcnt lgkmcnt(0)
	v_permlane16_swap_b32_e32 v99, v103
	v_add_f32_e32 v101, v99, v103
	v_mov_b32_e32 v103, v101
	v_cvt_pk_bf16_f32 v98, v78, v79
	v_cvt_pk_bf16_f32 v99, v74, v75
	global_store_dwordx2 v[58:59], v[96:97], off
	global_store_dwordx2 v[58:59], v[98:99], off offset:512
	s_waitcnt lgkmcnt(0)
	s_nop 0
	v_permlane32_swap_b32_e32 v101, v103
	v_add_f32_e32 v97, v101, v103
	v_fmamk_f32 v97, v97, 0x3a800000, v94
	v_mul_f32_e32 v98, 0x4f800000, v97
	v_cmp_gt_f32_e32 vcc, s10, v97
	v_cvt_pk_bf16_f32 v96, v82, v83
	s_nop 1
	v_cndmask_b32_e32 v101, v97, v98, vcc
	v_sqrt_f32_e32 v103, v101
	v_cvt_pk_bf16_f32 v97, v80, v81
	v_cvt_pk_bf16_f32 v98, v86, v87
	v_cvt_pk_bf16_f32 v99, v84, v85
	global_store_dwordx2 v[58:59], v[96:97], off offset:1024
	global_store_dwordx2 v[58:59], v[98:99], off offset:1536
	v_add_u32_e32 v104, -1, v103
	v_add_u32_e32 v105, 1, v103
	v_fma_f32 v106, -v104, v103, v101
	v_fma_f32 v107, -v105, v103, v101
	v_cmp_ge_f32_e64 s[0:1], 0, v106
	v_mul_f32_e32 v97, v49, v49
	v_mul_f32_e32 v98, v51, v51
	v_cndmask_b32_e64 v103, v103, v104, s[0:1]
	v_cmp_lt_f32_e64 s[0:1], 0, v107
	v_fmac_f32_e32 v97, v48, v48
	v_fmac_f32_e32 v98, v50, v50
	v_cndmask_b32_e64 v103, v103, v105, s[0:1]
	v_mul_f32_e32 v104, 0x37800000, v103
	v_cndmask_b32_e32 v103, v103, v104, vcc
	v_cmp_class_f32_e32 vcc, v101, v95
	v_add_f32_e32 v97, v97, v98
	s_nop 0
	v_cndmask_b32_e32 v101, v103, v101, vcc
	v_div_scale_f32 v103, s[0:1], v101, v101, 1.0
	v_rcp_f32_e32 v104, v103
	v_div_scale_f32 v58, vcc, 1.0, v101, 1.0
	v_fma_f32 v59, -v103, v104, 1.0
	v_fmac_f32_e32 v104, v59, v104
	v_mul_f32_e32 v59, v58, v104
	v_fma_f32 v96, -v103, v59, v58
	v_fmac_f32_e32 v59, v96, v104
	v_mul_f32_e32 v96, v77, v77
	v_fmac_f32_e32 v96, v76, v76
	v_add_f32_e32 v96, v102, v96
	v_add_f32_e32 v96, v100, v96
	v_add_f32_e32 v96, v97, v96
	s_nop 1
	v_fma_f32 v58, -v103, v59, v58
	v_div_fmas_f32 v58, v58, v104, v59
	v_div_fixup_f32 v58, v58, v101, 1.0
	v_pk_mul_f32 v[86:87], v[86:87], v[58:59] op_sel_hi:[1,0]
	s_waitcnt lgkmcnt(0)
	v_add_f32_dpp v59, v96, v96 quad_perm:[1,0,3,2] row_mask:0xf bank_mask:0xf
	s_nop 1
	v_pk_mul_f32 v[84:85], v[84:85], v[58:59] op_sel_hi:[1,0]
	v_pk_mul_f32 v[82:83], v[82:83], v[58:59] op_sel_hi:[1,0]
	v_pk_mul_f32 v[84:85], v[30:31], v[84:85]
	v_pk_mul_f32 v[82:83], v[24:25], v[82:83]
	s_waitcnt lgkmcnt(0)
	v_add_f32_dpp v59, v59, v59 quad_perm:[2,3,0,1] row_mask:0xf bank_mask:0xf
	s_nop 1
	v_pk_mul_f32 v[80:81], v[80:81], v[58:59] op_sel_hi:[1,0]
	v_pk_mul_f32 v[78:79], v[78:79], v[58:59] op_sel_hi:[1,0]
	v_pk_mul_f32 v[86:87], v[28:29], v[86:87]
	v_pk_mul_f32 v[78:79], v[20:21], v[78:79]
	s_waitcnt lgkmcnt(0)
	v_add_f32_dpp v59, v59, v59 row_half_mirror row_mask:0xf bank_mask:0xf
	s_nop 1
	v_pk_mul_f32 v[74:75], v[74:75], v[58:59] op_sel_hi:[1,0]
	v_pk_mul_f32 v[72:73], v[72:73], v[58:59] op_sel_hi:[1,0]
	v_pk_mul_f32 v[74:75], v[22:23], v[74:75]
	v_pk_mul_f32 v[80:81], v[26:27], v[80:81]
	s_waitcnt lgkmcnt(0)
	v_add_f32_dpp v98, v59, v59 row_mirror row_mask:0xf bank_mask:0xf
	v_mov_b32_e32 v99, v98
	v_pk_mul_f32 v[58:59], v[70:71], v[58:59] op_sel_hi:[1,0]
	v_pk_mul_f32 v[70:71], v[16:17], v[72:73]
	v_pk_mul_f32 v[58:59], v[18:19], v[58:59]
	v_cvt_pk_bf16_f32 v70, v70, v71
	s_waitcnt lgkmcnt(0)
	v_permlane16_swap_b32_e32 v98, v99
	v_add_f32_e32 v98, v98, v99
	ds_bpermute_b32 v99, v93, v98
	v_cvt_pk_bf16_f32 v71, v58, v59
	v_lshl_add_u64 v[96:97], v[54:55], 0, s[6:7]
	v_cvt_pk_bf16_f32 v72, v78, v79
	v_cvt_pk_bf16_f32 v73, v74, v75
	s_waitcnt lgkmcnt(0)
	v_add_f32_e32 v58, v98, v99
	v_fmamk_f32 v58, v58, 0x3a800000, v94
	v_mul_f32_e32 v59, 0x4f800000, v58
	v_cmp_gt_f32_e32 vcc, s10, v58
	global_store_dwordx2 v[96:97], v[70:71], off
	global_store_dwordx2 v[96:97], v[72:73], off offset:512
	s_mov_b64 s[6:7], -1
	v_cndmask_b32_e32 v58, v58, v59, vcc
	v_sqrt_f32_e32 v59, v58
	v_cvt_pk_bf16_f32 v70, v82, v83
	v_cvt_pk_bf16_f32 v71, v80, v81
	s_nop 0
	v_add_u32_e32 v72, -1, v59
	v_fma_f32 v73, -v72, v59, v58
	v_cmp_ge_f32_e64 s[0:1], 0, v73
	v_add_u32_e32 v73, 1, v59
	s_nop 0
	v_cndmask_b32_e64 v72, v59, v72, s[0:1]
	v_fma_f32 v59, -v73, v59, v58
	v_cmp_lt_f32_e64 s[0:1], 0, v59
	s_nop 1
	v_cndmask_b32_e64 v59, v72, v73, s[0:1]
	v_mul_f32_e32 v72, 0x37800000, v59
	v_cndmask_b32_e32 v59, v59, v72, vcc
	v_cmp_class_f32_e32 vcc, v58, v95
	v_cvt_pk_bf16_f32 v72, v86, v87
	v_cvt_pk_bf16_f32 v73, v84, v85
	global_store_dwordx2 v[96:97], v[70:71], off offset:1024
	global_store_dwordx2 v[96:97], v[72:73], off offset:1536
	s_nop 0
	v_cndmask_b32_e32 v58, v59, v58, vcc
	v_div_scale_f32 v59, s[0:1], v58, v58, 1.0
	v_rcp_f32_e32 v74, v59
	s_cselect_b64 s[0:1], -1, 0
	v_fma_f32 v70, -v59, v74, 1.0
	v_fmac_f32_e32 v74, v70, v74
	v_div_scale_f32 v70, vcc, 1.0, v58, 1.0
	v_mul_f32_e32 v71, v70, v74
	v_fma_f32 v72, -v59, v71, v70
	v_fmac_f32_e32 v71, v72, v74
	v_fma_f32 v59, -v59, v71, v70
	v_div_fmas_f32 v59, v59, v74, v71
	v_div_fixup_f32 v58, v59, v58, 1.0
	v_mul_f32_e32 v70, 0.5, v58
	v_pk_mul_f32 v[68:69], v[70:71], v[68:69] op_sel_hi:[0,1]
	v_pk_mul_f32 v[58:59], v[70:71], v[64:65] op_sel_hi:[0,1]
	v_pk_fma_f32 v[58:59], v[0:1], v[58:59], v[44:45]
	v_pk_fma_f32 v[44:45], v[2:3], v[68:69], v[46:47]
	v_pk_mul_f32 v[64:65], v[70:71], v[66:67] op_sel_hi:[0,1]
	v_pk_mul_f32 v[46:47], v[70:71], v[62:63] op_sel_hi:[0,1]
	v_pk_fma_f32 v[46:47], v[4:5], v[46:47], v[40:41]
	v_pk_fma_f32 v[40:41], v[6:7], v[64:65], v[42:43]
	v_pk_mul_f32 v[62:63], v[70:71], v[76:77] op_sel_hi:[0,1]
	v_pk_mul_f32 v[42:43], v[70:71], v[60:61] op_sel_hi:[0,1]
	s_waitcnt vmcnt(0)
	v_pk_fma_f32 v[42:43], v[8:9], v[42:43], v[36:37]
	v_pk_fma_f32 v[36:37], v[10:11], v[62:63], v[38:39]
	v_pk_mul_f32 v[50:51], v[70:71], v[50:51] op_sel_hi:[0,1]
	v_pk_mul_f32 v[38:39], v[70:71], v[48:49] op_sel_hi:[0,1]
	v_pk_fma_f32 v[38:39], v[12:13], v[38:39], v[32:33]
	v_pk_fma_f32 v[32:33], v[14:15], v[50:51], v[34:35]
	s_and_b64 vcc, exec, s[0:1]
	s_cbranch_vccnz .LBB0_405
	s_mov_b64 s[6:7], 0
.LBB0_405:
	s_andn2_b64 vcc, exec, s[6:7]
	s_cbranch_vccnz .LBB0_407
	s_ashr_i32 s5, s4, 31
	s_lshl_b64 s[6:7], s[4:5], 11
	v_lshl_add_u64 v[34:35], v[52:53], 0, s[6:7]
	v_cvt_pk_bf16_f32 v48, v58, v59
	v_cvt_pk_bf16_f32 v49, v44, v45
	v_cvt_pk_bf16_f32 v50, v46, v47
	v_cvt_pk_bf16_f32 v51, v40, v41
	global_store_dwordx2 v[34:35], v[48:49], off
	global_store_dwordx2 v[34:35], v[50:51], off offset:512
	s_nop 1
	v_cvt_pk_bf16_f32 v48, v42, v43
	v_cvt_pk_bf16_f32 v49, v36, v37
	v_cvt_pk_bf16_f32 v50, v38, v39
	v_cvt_pk_bf16_f32 v51, v32, v33
	global_store_dwordx2 v[34:35], v[48:49], off offset:1024
	global_store_dwordx2 v[34:35], v[50:51], off offset:1536
.LBB0_407:
	v_mul_f32_e32 v34, v58, v58
	v_mul_f32_e32 v35, v44, v44
	v_fmac_f32_e32 v34, v59, v59
	v_fmac_f32_e32 v35, v45, v45
	v_add_f32_e32 v34, v35, v34
	v_mul_f32_e32 v35, v46, v46
	v_mul_f32_e32 v48, v40, v40
	v_fmac_f32_e32 v35, v47, v47
	v_fmac_f32_e32 v48, v41, v41
	v_add_f32_e32 v35, v48, v35
	v_add_f32_e32 v34, v35, v34
	v_mul_f32_e32 v35, v42, v42
	v_mul_f32_e32 v48, v36, v36
	v_fmac_f32_e32 v35, v43, v43
	v_fmac_f32_e32 v48, v37, v37
	v_add_f32_e32 v35, v48, v35
	v_add_f32_e32 v34, v35, v34
	v_mul_f32_e32 v35, v38, v38
	v_mul_f32_e32 v48, v32, v32
	v_fmac_f32_e32 v35, v39, v39
	v_fmac_f32_e32 v48, v33, v33
	v_add_f32_e32 v35, v48, v35
	v_add_f32_e32 v34, v35, v34
	s_nop 1
	s_andn2_b64 vcc, exec, s[0:1]
	s_waitcnt lgkmcnt(0)
	v_add_f32_dpp v34, v34, v34 quad_perm:[1,0,3,2] row_mask:0xf bank_mask:0xf
	s_nop 1
	s_waitcnt lgkmcnt(0)
	v_add_f32_dpp v34, v34, v34 quad_perm:[2,3,0,1] row_mask:0xf bank_mask:0xf
	s_nop 1
	s_waitcnt lgkmcnt(0)
	v_add_f32_dpp v34, v34, v34 row_half_mirror row_mask:0xf bank_mask:0xf
	s_nop 1
	s_waitcnt lgkmcnt(0)
	v_add_f32_dpp v34, v34, v34 row_mirror row_mask:0xf bank_mask:0xf
	v_mov_b32_e32 v35, v34
	s_waitcnt lgkmcnt(0)
	s_nop 0
	v_permlane16_swap_b32_e32 v34, v35
	v_add_f32_e32 v34, v34, v35
	ds_bpermute_b32 v35, v93, v34
	s_cbranch_vccnz .LBB0_402
	s_waitcnt lgkmcnt(0)
	v_add_f32_e32 v34, v34, v35
	v_fmamk_f32 v34, v34, 0x3a800000, v94
	v_mul_f32_e32 v35, 0x4f800000, v34
	v_cmp_gt_f32_e32 vcc, s10, v34
	s_ashr_i32 s5, s4, 31
	s_nop 0
	v_cndmask_b32_e32 v34, v34, v35, vcc
	v_sqrt_f32_e32 v35, v34
	s_nop 0
	v_add_u32_e32 v48, -1, v35
	v_fma_f32 v50, -v48, v35, v34
	v_add_u32_e32 v49, 1, v35
	v_cmp_ge_f32_e64 s[0:1], 0, v50
	s_nop 1
	v_cndmask_b32_e64 v48, v35, v48, s[0:1]
	v_fma_f32 v35, -v49, v35, v34
	v_cmp_lt_f32_e64 s[0:1], 0, v35
	s_nop 1
	v_cndmask_b32_e64 v35, v48, v49, s[0:1]
	v_mul_f32_e32 v48, 0x37800000, v35
	v_cndmask_b32_e32 v35, v35, v48, vcc
	v_cmp_class_f32_e32 vcc, v34, v95
	s_nop 1
	v_cndmask_b32_e32 v34, v35, v34, vcc
	v_div_scale_f32 v35, s[0:1], v34, v34, 1.0
	v_rcp_f32_e32 v48, v35
	s_lshl_b64 s[0:1], s[4:5], 11
	v_fma_f32 v49, -v35, v48, 1.0
	v_fmac_f32_e32 v48, v49, v48
	v_div_scale_f32 v49, vcc, 1.0, v34, 1.0
	v_mul_f32_e32 v50, v49, v48
	v_fma_f32 v51, -v35, v50, v49
	v_fmac_f32_e32 v50, v51, v48
	v_fma_f32 v35, -v35, v50, v49
	v_div_fmas_f32 v35, v35, v48, v50
	v_div_fixup_f32 v34, v35, v34, 1.0
	v_pk_mul_f32 v[32:33], v[32:33], v[34:35] op_sel_hi:[1,0]
	v_pk_mul_f32 v[38:39], v[38:39], v[34:35] op_sel_hi:[1,0]
	v_pk_mul_f32 v[48:49], v[30:31], v[32:33]
	v_pk_mul_f32 v[32:33], v[42:43], v[34:35] op_sel_hi:[1,0]
	v_pk_mul_f32 v[36:37], v[36:37], v[34:35] op_sel_hi:[1,0]
	v_pk_mul_f32 v[42:43], v[24:25], v[32:33]
	v_pk_mul_f32 v[32:33], v[46:47], v[34:35] op_sel_hi:[1,0]
	v_pk_mul_f32 v[40:41], v[40:41], v[34:35] op_sel_hi:[1,0]
	v_pk_mul_f32 v[46:47], v[20:21], v[32:33]
	v_pk_mul_f32 v[32:33], v[58:59], v[34:35] op_sel_hi:[1,0]
	v_pk_mul_f32 v[34:35], v[44:45], v[34:35] op_sel_hi:[1,0]
	v_pk_mul_f32 v[32:33], v[16:17], v[32:33]
	v_pk_mul_f32 v[34:35], v[18:19], v[34:35]
	v_pk_mul_f32 v[40:41], v[22:23], v[40:41]
	v_lshl_add_u64 v[44:45], v[54:55], 0, s[0:1]
	v_cvt_pk_bf16_f32 v32, v32, v33
	v_cvt_pk_bf16_f32 v33, v34, v35
	v_cvt_pk_bf16_f32 v34, v46, v47
	v_cvt_pk_bf16_f32 v35, v40, v41
	v_pk_mul_f32 v[38:39], v[28:29], v[38:39]
	v_pk_mul_f32 v[36:37], v[26:27], v[36:37]
	global_store_dwordx2 v[44:45], v[32:33], off
	global_store_dwordx2 v[44:45], v[34:35], off offset:512
	s_nop 1
	v_cvt_pk_bf16_f32 v32, v42, v43
	v_cvt_pk_bf16_f32 v33, v36, v37
	v_cvt_pk_bf16_f32 v34, v38, v39
	v_cvt_pk_bf16_f32 v35, v48, v49
	global_store_dwordx2 v[44:45], v[32:33], off offset:1024
	global_store_dwordx2 v[44:45], v[34:35], off offset:1536
	s_branch .LBB0_402
